# P0 rebalance: W_q/W_kv conversion items assigned to the waves that had only 2 items (max per-wave item chain 4 -> 3)
# speedup vs baseline: 1.0235x; 1.0048x over previous
; __device__ __forceinline__ float sigmoidf_(float x) { return __builtin_amdgcn_rcpf(1.0f + __builtin_amdgcn_exp2f(-1.4426950408889634f * x)); }
; #define IN_w_in PTRF(4)
; #define IN_g_q PTRF(6)
; #define IN_w_q PTRF(7)
; #define IN_g_kv PTRF(8)
; __global__ void __launch_bounds__(512, 2) fwd_kernel(Args a) {
;     ...
;         for (int it = gw; it < NITEMS; it += NGW) {
;             int r = it;
;             if (r < I_ADA) {
;                 const int cb = r % 48, kc = r / 48, col = cb * 256 + lane * 4;
;                 f32x4 s0 = {0.f, 0.f, 0.f, 0.f}, s1 = {0.f, 0.f, 0.f, 0.f};
;                 const int kbeg = kc * (DMODEL / KC_ADA);
; #pragma unroll 16
;                 for (int k = kbeg; k < kbeg + DMODEL / KC_ADA; ++k) {
;                     const f32x4 wv = __builtin_nontemporal_load((const f32x4*)(wada_p + (size_t)k * NADA + col));
;                     const float c0 = c_p[k], c1 = c_p[DMODEL + k];
;                     const float a0 = c0 * sigmoidf_(c0), a1 = c1 * sigmoidf_(c1);
;                     s0 += wv * a0; s1 += wv * a1;
;                 }
;                 *(f32x4*)(part + (size_t)(kc * 2 + 0) * NADA + col) = s0; *(f32x4*)(part + (size_t)(kc * 2 + 1) * NADA + col) = s1;
;                 continue;
;             }
;             r -= I_ADA;
;             if (r < I_IN) { conv_item(IN_w_in, 2048, DIN, WinT, scr, r / 128, r % 128, lane, nullptr, map_win); continue; } r -= I_IN;
;             if (r < I_UP) { conv_item(IN_w_up, 2048, DFF, WupT, scr, r / 128, r % 128, lane, nullptr, map_id, true); continue; } r -= I_UP;
;             if (r < I_DN) { conv_item(IN_w_dn, 8192, DMODEL, WdnT, scr, r / 32, r % 32, lane, nullptr, map_id, true); continue; } r -= I_DN;
;             if (r < I_OUT) { conv_item(IN_w_out, 2048, DMODEL, WoutT, scr, r / 32, r % 32, lane, nullptr, map_id, true); continue; } r -= I_OUT;
;             if (r < I_BR) { conv_item(IN_w_bf, 1024, DMODEL, WbrT, scr, r / 32, r % 32, lane, nullptr, map_id, true); continue; } r -= I_BR;
;             if (r < I_BR) { conv_item(IN_w_bm, 1024, DMODEL, WbrT + (size_t)2048 * 1024, scr, r / 32, r % 32, lane, nullptr, map_id, true); continue; } r -= I_BR;
;             if (r < I_Q) { conv_item(IN_w_q, 512, QW, WqT, scr, r / 24, r % 24, lane, IN_g_q, map_wq); continue; } r -= I_Q;
;             conv_item(IN_w_kv, 256, KVW, WkvT, scr, r / 32, r % 32, lane, IN_g_kv, map_id);
;         }
.LBB0_209:
	s_cmp_eq_u32 s100, 1
	s_cbranch_scc1 .Lcv_ret
	s_cmp_eq_u32 s100, 2
	s_cbranch_scc1 .Lp0_rope
	s_mov_b32 s100, 2
	s_cmp_lt_u32 s96, 0x600
	s_cbranch_scc1 .Lp0_rope
	s_add_i32 s99, s96, 0x3800
	s_movk_i32 s101, 0x3f3f
	s_cmp_gt_i32 s99, s101
	s_cbranch_scc1 .Lp0_rope
	s_branch .Lp0_entry
